# grid barrier: the four group arrival counters moved into the second 128-byte line (offsets 128..224) so the 256 pollers of the top counter no longer share a line with the arrival atomics
# speedup vs baseline: 1.0528x; 1.0491x over previous
; DI void fast_grid_barrier(unsigned* ctr, unsigned target) {
;     asm volatile("s_waitcnt vmcnt(0)" ::: "memory");
;     __syncthreads();
;     if (threadIdx.x == 0) {
;         __builtin_amdgcn_fence(__ATOMIC_RELEASE, "agent");
;         asm volatile("s_waitcnt vmcnt(0)" ::: "memory");
;         __hip_atomic_fetch_add(ctr, 1u, __ATOMIC_RELAXED, __HIP_MEMORY_SCOPE_AGENT);
;         while (__hip_atomic_load(ctr, __ATOMIC_RELAXED, __HIP_MEMORY_SCOPE_AGENT) < target) __builtin_amdgcn_s_sleep(1);
;         __builtin_amdgcn_fence(__ATOMIC_ACQUIRE, "agent");
;         asm volatile("s_waitcnt vmcnt(0)" ::: "memory");
;     }
;     __syncthreads();
; }
.LBB0_4:
	s_cmp_le_i32 s70, s12
	s_cbranch_scc1 .LBB0_26
	v_readlane_b32 s0, v255, 4
	s_cmp_lg_u32 s70, s0
	s_mov_b64 s[0:1], -1
	s_waitcnt vmcnt(0)
	v_readlane_b32 s0, v255, 11
	s_add_i32 s4, s0, 1
	s_barrier
	s_mov_b64 s[0:1], exec
	v_readlane_b32 s6, v255, 12
	v_readlane_b32 s7, v255, 13
	s_and_b64 s[6:7], s[0:1], s[6:7]
	s_mov_b64 exec, s[6:7]
	s_cbranch_execz .LBB0_12
	buffer_wbl2 sc1
	s_waitcnt vmcnt(0)
	s_and_b32 s5, s2, 3
	s_lshl_b32 s8, s5, 5
	s_add_i32 s8, s8, 0x80
	v_mov_b32_e32 v0, 1
	v_mov_b32_e32 v1, s8
	global_atomic_add v2, v1, v0, s[14:15] sc0
	s_sub_i32 s9, s72, s5
	s_add_i32 s9, s9, 3
	s_lshr_b32 s9, s9, 2
	s_mul_i32 s9, s9, s4
	s_lshl_b32 s5, s4, 2
	s_waitcnt vmcnt(0)
	v_add_u32_e32 v2, 1, v2
	v_cmp_eq_u32_e32 vcc, s9, v2
	s_cbranch_vccz .Lgb_poll
	global_atomic_add v165, v0, s[14:15]
